# E40: P0 weight transposes: 16 gain scalars requested together after the weight loads (two variants) instead of 8 dependent pair round trips; on E35
# baseline (speedup 1.0000x reference)
.LBB0_20:
	s_andn2_b64 vcc, exec, s[0:1]
	s_cbranch_vccnz .LBB0_46
	s_and_b32 s37, s43, 0x3c0
	s_and_b32 s36, s33, 0x3c0
	v_or_b32_e32 v104, s37, v68
	s_lshl_b32 s26, s36, 2
	v_lshl_add_u64 v[2:3], v[96:97], 0, s[26:27]
	v_lshlrev_b32_e32 v70, 12, v104
	v_lshl_add_u64 v[2:3], v[2:3], 0, v[70:71]
	v_add_co_u32_e32 v4, vcc, 0x4000, v2
	v_cndmask_b32_e64 v70, 0, 1, s[30:31]
	s_nop 0
	v_addc_co_u32_e32 v5, vcc, 0, v3, vcc
	global_load_dwordx4 v[62:65], v[2:3], off nt
	global_load_dwordx4 v[58:61], v[4:5], off nt
	v_add_co_u32_e32 v4, vcc, 0x8000, v2
	v_cmp_ne_u32_e64 s[0:1], 1, v70
	s_nop 0
	v_addc_co_u32_e32 v5, vcc, 0, v3, vcc
	v_add_co_u32_e32 v6, vcc, 0xc000, v2
	v_add_lshl_u32 v95, s37, v68, 2
	s_nop 0
	v_addc_co_u32_e32 v7, vcc, 0, v3, vcc
	global_load_dwordx4 v[54:57], v[4:5], off nt
	global_load_dwordx4 v[50:53], v[6:7], off nt
	v_add_co_u32_e32 v4, vcc, 0x10000, v2
	s_nop 1
	v_addc_co_u32_e32 v5, vcc, 0, v3, vcc
	v_add_co_u32_e32 v6, vcc, 0x14000, v2
	s_nop 1
	v_addc_co_u32_e32 v7, vcc, 0, v3, vcc
	global_load_dwordx4 v[46:49], v[4:5], off nt
	global_load_dwordx4 v[42:45], v[6:7], off nt
	v_add_co_u32_e32 v4, vcc, 0x18000, v2
	s_nop 1
	v_addc_co_u32_e32 v5, vcc, 0, v3, vcc
	v_add_co_u32_e32 v6, vcc, 0x1c000, v2
	s_nop 1
	v_addc_co_u32_e32 v7, vcc, 0, v3, vcc
	global_load_dwordx4 v[38:41], v[4:5], off nt
	global_load_dwordx4 v[34:37], v[6:7], off nt
	v_add_co_u32_e32 v4, vcc, 0x20000, v2
	s_nop 1
	v_addc_co_u32_e32 v5, vcc, 0, v3, vcc
	v_add_co_u32_e32 v6, vcc, 0x24000, v2
	s_nop 1
	v_addc_co_u32_e32 v7, vcc, 0, v3, vcc
	global_load_dwordx4 v[30:33], v[4:5], off nt
	global_load_dwordx4 v[26:29], v[6:7], off nt
	v_add_co_u32_e32 v4, vcc, 0x28000, v2
	s_nop 1
	v_addc_co_u32_e32 v5, vcc, 0, v3, vcc
	v_add_co_u32_e32 v6, vcc, 0x2c000, v2
	s_nop 1
	v_addc_co_u32_e32 v7, vcc, 0, v3, vcc
	global_load_dwordx4 v[22:25], v[4:5], off nt
	global_load_dwordx4 v[18:21], v[6:7], off nt
	v_add_co_u32_e32 v4, vcc, 0x30000, v2
	s_nop 1
	v_addc_co_u32_e32 v5, vcc, 0, v3, vcc
	v_add_co_u32_e32 v6, vcc, 0x34000, v2
	s_nop 1
	v_addc_co_u32_e32 v7, vcc, 0, v3, vcc
	global_load_dwordx4 v[14:17], v[4:5], off nt
	global_load_dwordx4 v[10:13], v[6:7], off nt
	v_add_co_u32_e32 v4, vcc, 0x38000, v2
	s_nop 1
	v_addc_co_u32_e32 v5, vcc, 0, v3, vcc
	v_add_co_u32_e32 v2, vcc, 0x3c000, v2
	s_nop 1
	v_addc_co_u32_e32 v3, vcc, 0, v3, vcc
	global_load_dwordx4 v[6:9], v[4:5], off nt
	s_nop 0
	global_load_dwordx4 v[2:5], v[2:3], off nt
	s_andn2_b64 vcc, exec, s[30:31]
	s_cbranch_vccnz .LBB0_79
	v_lshlrev_b32_e32 v70, 2, v104
	global_load_dword v166, v70, s[16:17]
	global_load_dword v167, v95, s[16:17] offset:16
	global_load_dword v168, v95, s[16:17] offset:32
	global_load_dword v169, v95, s[16:17] offset:48
	global_load_dword v170, v95, s[16:17] offset:64
	global_load_dword v171, v95, s[16:17] offset:80
	global_load_dword v172, v95, s[16:17] offset:96
	global_load_dword v173, v95, s[16:17] offset:112
	global_load_dword v174, v95, s[16:17] offset:128
	global_load_dword v175, v95, s[16:17] offset:144
	global_load_dword v176, v95, s[16:17] offset:160
	global_load_dword v177, v95, s[16:17] offset:176
	global_load_dword v178, v95, s[16:17] offset:192
	global_load_dword v179, v95, s[16:17] offset:208
	global_load_dword v180, v95, s[16:17] offset:224
	global_load_dword v181, v95, s[16:17] offset:240
	v_add_u32_e32 v144, v67, v106
	s_waitcnt vmcnt(0)
	v_mov_b32_e32 v104, v166
	v_mov_b32_e32 v70, v167
	v_pk_mul_f32 v[142:143], v[62:63], v[104:105] op_sel_hi:[1,0]
	v_pk_mul_f32 v[104:105], v[64:65], v[104:105] op_sel_hi:[1,0]
	ds_write2_b32 v144, v142, v143 offset1:1
	ds_write2_b32 v144, v104, v105 offset0:2 offset1:3
	s_cbranch_execnz .LBB0_24

.LBB0_24:
	s_waitcnt vmcnt(0)
	v_pk_mul_f32 v[58:59], v[58:59], v[70:71] op_sel_hi:[1,0]
	v_add_u32_e32 v62, v67, v117
	ds_write2_b32 v62, v58, v59 offset1:1
	v_pk_mul_f32 v[58:59], v[60:61], v[70:71] op_sel_hi:[1,0]
	s_and_b64 vcc, exec, s[0:1]
	ds_write2_b32 v62, v58, v59 offset0:2 offset1:3
	s_cbranch_vccnz .LBB0_80
	v_mov_b32_e32 v60, v168
	v_mov_b32_e32 v58, v169
	v_add_u32_e32 v59, v67, v119
	s_waitcnt vmcnt(1)
	v_pk_mul_f32 v[62:63], v[54:55], v[60:61] op_sel_hi:[1,0]
	v_pk_mul_f32 v[60:61], v[56:57], v[60:61] op_sel_hi:[1,0]
	ds_write2_b32 v59, v62, v63 offset1:1
	ds_write2_b32 v59, v60, v61 offset0:2 offset1:3
	s_cbranch_execnz .LBB0_27

.LBB0_27:
	s_waitcnt vmcnt(0)
	v_pk_mul_f32 v[50:51], v[50:51], v[58:59] op_sel_hi:[1,0]
	v_add_u32_e32 v54, v67, v121
	ds_write2_b32 v54, v50, v51 offset1:1
	v_pk_mul_f32 v[50:51], v[52:53], v[58:59] op_sel_hi:[1,0]
	s_and_b64 vcc, exec, s[0:1]
	ds_write2_b32 v54, v50, v51 offset0:2 offset1:3
	s_cbranch_vccnz .LBB0_81
	v_mov_b32_e32 v52, v170
	v_mov_b32_e32 v50, v171
	v_add_u32_e32 v51, v67, v123
	s_waitcnt vmcnt(1)
	v_pk_mul_f32 v[54:55], v[46:47], v[52:53] op_sel_hi:[1,0]
	v_pk_mul_f32 v[52:53], v[48:49], v[52:53] op_sel_hi:[1,0]
	ds_write2_b32 v51, v54, v55 offset1:1
	ds_write2_b32 v51, v52, v53 offset0:2 offset1:3
	s_cbranch_execnz .LBB0_30

.LBB0_30:
	s_waitcnt vmcnt(0)
	v_pk_mul_f32 v[42:43], v[42:43], v[50:51] op_sel_hi:[1,0]
	v_add_u32_e32 v46, v67, v125
	ds_write2_b32 v46, v42, v43 offset1:1
	v_pk_mul_f32 v[42:43], v[44:45], v[50:51] op_sel_hi:[1,0]
	s_and_b64 vcc, exec, s[0:1]
	ds_write2_b32 v46, v42, v43 offset0:2 offset1:3
	s_cbranch_vccnz .LBB0_82
	v_mov_b32_e32 v44, v172
	v_mov_b32_e32 v42, v173
	v_add_u32_e32 v43, v67, v127
	s_waitcnt vmcnt(1)
	v_pk_mul_f32 v[46:47], v[38:39], v[44:45] op_sel_hi:[1,0]
	v_pk_mul_f32 v[44:45], v[40:41], v[44:45] op_sel_hi:[1,0]
	ds_write2_b32 v43, v46, v47 offset1:1
	ds_write2_b32 v43, v44, v45 offset0:2 offset1:3
	s_cbranch_execnz .LBB0_33

.LBB0_33:
	s_waitcnt vmcnt(0)
	v_pk_mul_f32 v[34:35], v[34:35], v[42:43] op_sel_hi:[1,0]
	v_add_u32_e32 v38, v67, v129
	ds_write2_b32 v38, v34, v35 offset1:1
	v_pk_mul_f32 v[34:35], v[36:37], v[42:43] op_sel_hi:[1,0]
	s_and_b64 vcc, exec, s[0:1]
	ds_write2_b32 v38, v34, v35 offset0:2 offset1:3
	s_cbranch_vccnz .LBB0_83
	v_mov_b32_e32 v36, v174
	v_mov_b32_e32 v34, v175
	v_add_u32_e32 v35, v67, v131
	s_waitcnt vmcnt(1)
	v_pk_mul_f32 v[38:39], v[30:31], v[36:37] op_sel_hi:[1,0]
	v_pk_mul_f32 v[36:37], v[32:33], v[36:37] op_sel_hi:[1,0]
	ds_write2_b32 v35, v38, v39 offset1:1
	ds_write2_b32 v35, v36, v37 offset0:2 offset1:3
	s_cbranch_execnz .LBB0_36

.LBB0_36:
	s_waitcnt vmcnt(0)
	v_pk_mul_f32 v[26:27], v[26:27], v[34:35] op_sel_hi:[1,0]
	v_add_u32_e32 v30, v67, v132
	ds_write2_b32 v30, v26, v27 offset1:1
	v_pk_mul_f32 v[26:27], v[28:29], v[34:35] op_sel_hi:[1,0]
	s_and_b64 vcc, exec, s[0:1]
	ds_write2_b32 v30, v26, v27 offset0:2 offset1:3
	s_cbranch_vccnz .LBB0_84
	v_mov_b32_e32 v28, v176
	v_mov_b32_e32 v26, v177
	v_add_u32_e32 v27, v67, v133
	s_waitcnt vmcnt(1)
	v_pk_mul_f32 v[30:31], v[22:23], v[28:29] op_sel_hi:[1,0]
	v_pk_mul_f32 v[28:29], v[24:25], v[28:29] op_sel_hi:[1,0]
	ds_write2_b32 v27, v30, v31 offset1:1
	ds_write2_b32 v27, v28, v29 offset0:2 offset1:3
	s_cbranch_execnz .LBB0_39

.LBB0_39:
	s_waitcnt vmcnt(0)
	v_pk_mul_f32 v[22:23], v[18:19], v[26:27] op_sel_hi:[1,0]
	v_add_u32_e32 v19, v67, v134
	v_pk_mul_f32 v[20:21], v[20:21], v[26:27] op_sel_hi:[1,0]
	ds_write2_b32 v19, v20, v21 offset0:2 offset1:3
	s_and_b64 vcc, exec, s[0:1]
	v_add_u32_e32 v20, 0x410, v19
	v_add_u32_e32 v21, 0x418, v19
	ds_write2_b32 v19, v22, v23 offset1:1
	s_cbranch_vccnz .LBB0_85
	v_mov_b32_e32 v22, v178
	v_mov_b32_e32 v18, v179
	s_waitcnt vmcnt(1)
	v_pk_mul_f32 v[24:25], v[14:15], v[22:23] op_sel_hi:[1,0]
	v_pk_mul_f32 v[22:23], v[16:17], v[22:23] op_sel_hi:[1,0]
	ds_write2_b32 v20, v24, v25 offset1:1
	ds_write2_b32 v21, v22, v23 offset1:1
	s_cbranch_execnz .LBB0_42

.LBB0_42:
	s_waitcnt vmcnt(0)
	v_pk_mul_f32 v[10:11], v[10:11], v[18:19] op_sel_hi:[1,0]
	v_add_u32_e32 v14, 0x820, v19
	ds_write2_b32 v14, v10, v11 offset1:1
	v_pk_mul_f32 v[10:11], v[12:13], v[18:19] op_sel_hi:[1,0]
	v_add_u32_e32 v12, 0x828, v19
	ds_write2_b32 v12, v10, v11 offset1:1
	s_and_b64 vcc, exec, s[0:1]
	v_add_u32_e32 v11, 0xc30, v19
	v_add_u32_e32 v12, 0xc38, v19
	s_cbranch_vccnz .LBB0_86
	v_mov_b32_e32 v14, v180
	v_mov_b32_e32 v10, v181
	s_waitcnt vmcnt(1)
	v_pk_mul_f32 v[16:17], v[6:7], v[14:15] op_sel_hi:[1,0]
	v_pk_mul_f32 v[14:15], v[8:9], v[14:15] op_sel_hi:[1,0]
	ds_write2_b32 v11, v16, v17 offset1:1
	ds_write2_b32 v12, v14, v15 offset1:1
	s_cbranch_execnz .LBB0_45

.LBB0_47:
	s_andn2_b64 vcc, exec, s[0:1]
	s_cbranch_vccnz .LBB0_12
	s_ashr_i32 s0, s90, 31
	s_lshr_b32 s0, s0, 28
	s_add_i32 s0, s90, s0
	s_ashr_i32 s0, s0, 4
	s_lshl_b32 s18, s0, 6
	s_lshl_b32 s26, s0, 10
	v_or_b32_e32 v104, s18, v68
	s_sub_i32 s0, s33, s26
	v_or_b32_e32 v6, 4, v104
	s_ashr_i32 s1, s0, 31
	v_ashrrev_i32_e32 v105, 31, v104
	v_ashrrev_i32_e32 v7, 31, v6
	v_lshl_add_u64 v[2:3], s[0:1], 2, v[100:101]
	v_lshlrev_b64 v[4:5], 12, v[104:105]
	v_lshlrev_b64 v[6:7], 12, v[6:7]
	v_lshl_add_u64 v[4:5], v[2:3], 0, v[4:5]
	v_lshl_add_u64 v[6:7], v[2:3], 0, v[6:7]
	global_load_dwordx4 v[62:65], v[4:5], off nt
	global_load_dwordx4 v[58:61], v[6:7], off nt
	v_or_b32_e32 v4, 8, v104
	v_or_b32_e32 v6, 12, v104
	v_ashrrev_i32_e32 v5, 31, v4
	v_ashrrev_i32_e32 v7, 31, v6
	v_lshlrev_b64 v[4:5], 12, v[4:5]
	v_lshlrev_b64 v[6:7], 12, v[6:7]
	v_lshl_add_u64 v[4:5], v[2:3], 0, v[4:5]
	v_lshl_add_u64 v[6:7], v[2:3], 0, v[6:7]
	global_load_dwordx4 v[54:57], v[4:5], off nt
	global_load_dwordx4 v[50:53], v[6:7], off nt
	v_or_b32_e32 v4, 16, v104
	v_or_b32_e32 v6, 20, v104
	v_ashrrev_i32_e32 v5, 31, v4
	v_ashrrev_i32_e32 v7, 31, v6
	v_lshlrev_b64 v[4:5], 12, v[4:5]
	v_lshlrev_b64 v[6:7], 12, v[6:7]
	v_lshl_add_u64 v[4:5], v[2:3], 0, v[4:5]
	v_lshl_add_u64 v[6:7], v[2:3], 0, v[6:7]
	global_load_dwordx4 v[46:49], v[4:5], off nt
	global_load_dwordx4 v[42:45], v[6:7], off nt
	v_or_b32_e32 v4, 24, v104
	v_or_b32_e32 v6, 28, v104
	v_ashrrev_i32_e32 v5, 31, v4
	v_ashrrev_i32_e32 v7, 31, v6
	v_lshlrev_b64 v[4:5], 12, v[4:5]
	v_lshlrev_b64 v[6:7], 12, v[6:7]
	v_lshl_add_u64 v[4:5], v[2:3], 0, v[4:5]
	v_lshl_add_u64 v[6:7], v[2:3], 0, v[6:7]
	global_load_dwordx4 v[38:41], v[4:5], off nt
	global_load_dwordx4 v[34:37], v[6:7], off nt
	v_or_b32_e32 v4, 32, v104
	v_or_b32_e32 v6, 36, v104
	v_ashrrev_i32_e32 v5, 31, v4
	v_ashrrev_i32_e32 v7, 31, v6
	v_lshlrev_b64 v[4:5], 12, v[4:5]
	v_lshlrev_b64 v[6:7], 12, v[6:7]
	v_lshl_add_u64 v[4:5], v[2:3], 0, v[4:5]
	v_lshl_add_u64 v[6:7], v[2:3], 0, v[6:7]
	global_load_dwordx4 v[30:33], v[4:5], off nt
	global_load_dwordx4 v[26:29], v[6:7], off nt
	v_or_b32_e32 v4, 40, v104
	v_or_b32_e32 v6, 44, v104
	v_ashrrev_i32_e32 v5, 31, v4
	v_ashrrev_i32_e32 v7, 31, v6
	v_lshlrev_b64 v[4:5], 12, v[4:5]
	v_lshlrev_b64 v[6:7], 12, v[6:7]
	v_lshl_add_u64 v[4:5], v[2:3], 0, v[4:5]
	v_lshl_add_u64 v[6:7], v[2:3], 0, v[6:7]
	global_load_dwordx4 v[22:25], v[4:5], off nt
	global_load_dwordx4 v[18:21], v[6:7], off nt
	v_or_b32_e32 v4, 48, v104
	v_or_b32_e32 v6, 52, v104
	v_ashrrev_i32_e32 v5, 31, v4
	v_ashrrev_i32_e32 v7, 31, v6
	v_lshlrev_b64 v[4:5], 12, v[4:5]
	v_lshlrev_b64 v[6:7], 12, v[6:7]
	v_lshl_add_u64 v[4:5], v[2:3], 0, v[4:5]
	v_lshl_add_u64 v[6:7], v[2:3], 0, v[6:7]
	global_load_dwordx4 v[14:17], v[4:5], off nt
	global_load_dwordx4 v[10:13], v[6:7], off nt
	v_or_b32_e32 v4, 56, v104
	v_or_b32_e32 v6, 60, v104
	v_ashrrev_i32_e32 v5, 31, v4
	v_ashrrev_i32_e32 v7, 31, v6
	v_lshlrev_b64 v[4:5], 12, v[4:5]
	v_lshlrev_b64 v[6:7], 12, v[6:7]
	v_lshl_add_u64 v[4:5], v[2:3], 0, v[4:5]
	v_lshl_add_u64 v[2:3], v[2:3], 0, v[6:7]
	global_load_dwordx4 v[6:9], v[4:5], off nt
	s_nop 0
	global_load_dwordx4 v[2:5], v[2:3], off nt
	v_cndmask_b32_e64 v70, 0, 1, s[34:35]
	v_cmp_ne_u32_e64 s[0:1], 1, v70
	s_andn2_b64 vcc, exec, s[34:35]
	v_add_u32_e32 v95, v67, v106
	s_cbranch_vccnz .LBB0_71
	s_ashr_i32 s19, s18, 31
	v_lshl_add_u64 v[104:105], v[104:105], 2, s[50:51]
	v_lshl_add_u64 v[142:143], s[18:19], 0, v[68:69]
	global_load_dword v166, v[104:105], off
	v_lshl_add_u64 v[142:143], v[142:143], 2, s[50:51]
	global_load_dword v167, v[142:143], off offset:16
	global_load_dword v168, v[142:143], off offset:32
	global_load_dword v169, v[142:143], off offset:48
	global_load_dword v170, v[142:143], off offset:64
	global_load_dword v171, v[142:143], off offset:80
	global_load_dword v172, v[142:143], off offset:96
	global_load_dword v173, v[142:143], off offset:112
	global_load_dword v174, v[142:143], off offset:128
	global_load_dword v175, v[142:143], off offset:144
	global_load_dword v176, v[142:143], off offset:160
	global_load_dword v177, v[142:143], off offset:176
	global_load_dword v178, v[142:143], off offset:192
	global_load_dword v179, v[142:143], off offset:208
	global_load_dword v180, v[142:143], off offset:224
	global_load_dword v181, v[142:143], off offset:240
	s_waitcnt vmcnt(0)
	v_mov_b32_e32 v104, v166
	v_mov_b32_e32 v70, v167
	v_pk_mul_f32 v[142:143], v[62:63], v[104:105] op_sel_hi:[1,0]
	v_pk_mul_f32 v[104:105], v[64:65], v[104:105] op_sel_hi:[1,0]
	ds_write2_b32 v95, v142, v143 offset1:1
	ds_write2_b32 v95, v104, v105 offset0:2 offset1:3
	s_cbranch_execnz .LBB0_51

.LBB0_51:
	s_waitcnt vmcnt(0)
	v_pk_mul_f32 v[58:59], v[58:59], v[70:71] op_sel_hi:[1,0]
	v_add_u32_e32 v62, v67, v117
	ds_write2_b32 v62, v58, v59 offset1:1
	v_pk_mul_f32 v[58:59], v[60:61], v[70:71] op_sel_hi:[1,0]
	ds_write2_b32 v62, v58, v59 offset0:2 offset1:3
	s_and_b64 vcc, exec, s[0:1]
	v_add_u32_e32 v59, v67, v119
	s_cbranch_vccnz .LBB0_72
	s_ashr_i32 s19, s18, 31
	v_lshl_add_u64 v[60:61], s[18:19], 0, v[68:69]
	v_lshl_add_u64 v[60:61], v[60:61], 2, s[50:51]
	v_mov_b32_e32 v62, v168
	v_mov_b32_e32 v58, v169
	s_waitcnt vmcnt(1)
	v_pk_mul_f32 v[60:61], v[54:55], v[62:63] op_sel_hi:[1,0]
	v_pk_mul_f32 v[62:63], v[56:57], v[62:63] op_sel_hi:[1,0]
	ds_write2_b32 v59, v60, v61 offset1:1
	ds_write2_b32 v59, v62, v63 offset0:2 offset1:3
	s_cbranch_execnz .LBB0_54

.LBB0_54:
	s_waitcnt vmcnt(0)
	v_pk_mul_f32 v[50:51], v[50:51], v[58:59] op_sel_hi:[1,0]
	v_add_u32_e32 v54, v67, v121
	ds_write2_b32 v54, v50, v51 offset1:1
	v_pk_mul_f32 v[50:51], v[52:53], v[58:59] op_sel_hi:[1,0]
	ds_write2_b32 v54, v50, v51 offset0:2 offset1:3
	s_and_b64 vcc, exec, s[0:1]
	v_add_u32_e32 v51, v67, v123
	s_cbranch_vccnz .LBB0_73
	s_ashr_i32 s19, s18, 31
	v_lshl_add_u64 v[52:53], s[18:19], 0, v[68:69]
	v_lshl_add_u64 v[52:53], v[52:53], 2, s[50:51]
	v_mov_b32_e32 v54, v170
	v_mov_b32_e32 v50, v171
	s_waitcnt vmcnt(1)
	v_pk_mul_f32 v[52:53], v[46:47], v[54:55] op_sel_hi:[1,0]
	v_pk_mul_f32 v[54:55], v[48:49], v[54:55] op_sel_hi:[1,0]
	ds_write2_b32 v51, v52, v53 offset1:1
	ds_write2_b32 v51, v54, v55 offset0:2 offset1:3
	s_cbranch_execnz .LBB0_57

.LBB0_57:
	s_waitcnt vmcnt(0)
	v_pk_mul_f32 v[42:43], v[42:43], v[50:51] op_sel_hi:[1,0]
	v_add_u32_e32 v46, v67, v125
	ds_write2_b32 v46, v42, v43 offset1:1
	v_pk_mul_f32 v[42:43], v[44:45], v[50:51] op_sel_hi:[1,0]
	ds_write2_b32 v46, v42, v43 offset0:2 offset1:3
	s_and_b64 vcc, exec, s[0:1]
	v_add_u32_e32 v43, v67, v127
	s_cbranch_vccnz .LBB0_74
	s_ashr_i32 s19, s18, 31
	v_lshl_add_u64 v[44:45], s[18:19], 0, v[68:69]
	v_lshl_add_u64 v[44:45], v[44:45], 2, s[50:51]
	v_mov_b32_e32 v46, v172
	v_mov_b32_e32 v42, v173
	s_waitcnt vmcnt(1)
	v_pk_mul_f32 v[44:45], v[38:39], v[46:47] op_sel_hi:[1,0]
	v_pk_mul_f32 v[46:47], v[40:41], v[46:47] op_sel_hi:[1,0]
	ds_write2_b32 v43, v44, v45 offset1:1
	ds_write2_b32 v43, v46, v47 offset0:2 offset1:3
	s_cbranch_execnz .LBB0_60

.LBB0_60:
	s_waitcnt vmcnt(0)
	v_pk_mul_f32 v[34:35], v[34:35], v[42:43] op_sel_hi:[1,0]
	v_add_u32_e32 v38, v67, v129
	ds_write2_b32 v38, v34, v35 offset1:1
	v_pk_mul_f32 v[34:35], v[36:37], v[42:43] op_sel_hi:[1,0]
	ds_write2_b32 v38, v34, v35 offset0:2 offset1:3
	s_and_b64 vcc, exec, s[0:1]
	v_add_u32_e32 v35, v67, v131
	s_cbranch_vccnz .LBB0_75
	s_ashr_i32 s19, s18, 31
	v_lshl_add_u64 v[36:37], s[18:19], 0, v[68:69]
	v_lshl_add_u64 v[36:37], v[36:37], 2, s[50:51]
	v_mov_b32_e32 v38, v174
	v_mov_b32_e32 v34, v175
	s_waitcnt vmcnt(1)
	v_pk_mul_f32 v[36:37], v[30:31], v[38:39] op_sel_hi:[1,0]
	v_pk_mul_f32 v[38:39], v[32:33], v[38:39] op_sel_hi:[1,0]
	ds_write2_b32 v35, v36, v37 offset1:1
	ds_write2_b32 v35, v38, v39 offset0:2 offset1:3
	s_cbranch_execnz .LBB0_63

.LBB0_63:
	s_waitcnt vmcnt(0)
	v_pk_mul_f32 v[26:27], v[26:27], v[34:35] op_sel_hi:[1,0]
	v_add_u32_e32 v30, v67, v132
	ds_write2_b32 v30, v26, v27 offset1:1
	v_pk_mul_f32 v[26:27], v[28:29], v[34:35] op_sel_hi:[1,0]
	ds_write2_b32 v30, v26, v27 offset0:2 offset1:3
	s_and_b64 vcc, exec, s[0:1]
	v_add_u32_e32 v27, v67, v133
	s_cbranch_vccnz .LBB0_76
	s_ashr_i32 s19, s18, 31
	v_lshl_add_u64 v[28:29], s[18:19], 0, v[68:69]
	v_lshl_add_u64 v[28:29], v[28:29], 2, s[50:51]
	v_mov_b32_e32 v30, v176
	v_mov_b32_e32 v26, v177
	s_waitcnt vmcnt(1)
	v_pk_mul_f32 v[28:29], v[22:23], v[30:31] op_sel_hi:[1,0]
	v_pk_mul_f32 v[30:31], v[24:25], v[30:31] op_sel_hi:[1,0]
	ds_write2_b32 v27, v28, v29 offset1:1
	ds_write2_b32 v27, v30, v31 offset0:2 offset1:3
	s_cbranch_execnz .LBB0_66

.LBB0_66:
	s_waitcnt vmcnt(0)
	v_pk_mul_f32 v[22:23], v[18:19], v[26:27] op_sel_hi:[1,0]
	v_add_u32_e32 v19, v67, v134
	v_pk_mul_f32 v[20:21], v[20:21], v[26:27] op_sel_hi:[1,0]
	ds_write2_b32 v19, v20, v21 offset0:2 offset1:3
	s_and_b64 vcc, exec, s[0:1]
	v_add_u32_e32 v20, 0x410, v19
	v_add_u32_e32 v21, 0x418, v19
	ds_write2_b32 v19, v22, v23 offset1:1
	s_cbranch_vccnz .LBB0_77
	s_ashr_i32 s19, s18, 31
	v_lshl_add_u64 v[22:23], s[18:19], 0, v[68:69]
	v_lshl_add_u64 v[22:23], v[22:23], 2, s[50:51]
	v_mov_b32_e32 v24, v178
	v_mov_b32_e32 v18, v179
	s_waitcnt vmcnt(1)
	v_pk_mul_f32 v[22:23], v[14:15], v[24:25] op_sel_hi:[1,0]
	v_pk_mul_f32 v[24:25], v[16:17], v[24:25] op_sel_hi:[1,0]
	ds_write2_b32 v20, v22, v23 offset1:1
	ds_write2_b32 v21, v24, v25 offset1:1
	s_cbranch_execnz .LBB0_69

.LBB0_69:
	s_waitcnt vmcnt(0)
	v_pk_mul_f32 v[10:11], v[10:11], v[18:19] op_sel_hi:[1,0]
	v_add_u32_e32 v14, 0x820, v19
	ds_write2_b32 v14, v10, v11 offset1:1
	v_pk_mul_f32 v[10:11], v[12:13], v[18:19] op_sel_hi:[1,0]
	v_add_u32_e32 v12, 0x828, v19
	ds_write2_b32 v12, v10, v11 offset1:1
	s_and_b64 vcc, exec, s[0:1]
	v_add_u32_e32 v11, 0xc30, v19
	v_add_u32_e32 v12, 0xc38, v19
	s_cbranch_vccnz .LBB0_78
	s_ashr_i32 s19, s18, 31
	v_lshl_add_u64 v[14:15], s[18:19], 0, v[68:69]
	v_lshl_add_u64 v[14:15], v[14:15], 2, s[50:51]
	v_mov_b32_e32 v16, v180
	v_mov_b32_e32 v10, v181
	s_waitcnt vmcnt(1)
	v_pk_mul_f32 v[14:15], v[6:7], v[16:17] op_sel_hi:[1,0]
	v_pk_mul_f32 v[16:17], v[8:9], v[16:17] op_sel_hi:[1,0]
	ds_write2_b32 v11, v14, v15 offset1:1
	ds_write2_b32 v12, v16, v17 offset1:1
	s_cbranch_execnz .LBB0_11
	s_branch .LBB0_10
